# NSA selected/window step heads: tile-index reads, next-tile address read and the 8 K-fragment LDS reads issued together (one exposed LDS round trip per step instead of 2-3)
# baseline (speedup 1.0000x reference)
; #define LAS __attribute__((address_space(3)))
; #define MFMA32(a, b, c) __builtin_amdgcn_mfma_f32_32x32x16_bf16((a), (b), (c), 0, 0, 0)
; #define SBAR() __builtin_amdgcn_sched_barrier(0)
; #define NS_GLOAD(k_, KR, VR) do { const int jj = __builtin_amdgcn_readfirstlane(jl[(k_)]); KR = *(const u32x4*)(kg + (size_t)(64 * jj + sr) * pitch + sc * 8); VR = *(const u32x4*)(vg + (size_t)(64 * jj + sr) * pitch + sc * 8); } while (0)
; #define NS_LSTORE(st_, KR, VR) do { lds8* b = lds + (st_) * NS_STAGE; *(LAS u32x4*)(b + sr * NS_STR + sc * 16) = KR; *(LAS u32x4*)(b + 64 * NS_STR + sr * NS_STR + sc * 16) = VR; } while (0)
; template <int KSTR> DI void qk64b(f32x16& s0, f32x16& s1, const lds8* kp, const bf16x8 (&q)[4], float bias) {
;   bf16x8 a[8];
; #pragma unroll
;   for (int ks = 0; ks < 4; ++ks) { a[2 * ks] = *(const LAS bf16x8*)(kp + ks * 32); a[2 * ks + 1] = *(const LAS bf16x8*)(kp + 32 * KSTR + ks * 32); }
; #pragma unroll
;   for (int i = 0; i < 16; ++i) { s0[i] = bias; s1[i] = bias; }
;   SBAR();
;   __builtin_amdgcn_s_setprio(1);
; #pragma unroll
;   for (int ks = 0; ks < 4; ++ks) { s0 = MFMA32(a[2 * ks], q[ks], s0); s1 = MFMA32(a[2 * ks + 1], q[ks], s1); }
;   __builtin_amdgcn_s_setprio(0);
;   SBAR();
; }
; template <int MODE>
; DI void nsa_branch(lds8* lds, const bf16_t* kg, const bf16_t* vg, int pitch, unsigned tiles, const bf16x8 (&q)[4], int qpos, unsigned mybits, int blk,
;                    f32x16 (&O)[2], float& muse, float& l, int tid, int lane, int grp, CmpCap& cap) {
;     ...
;   NS_GLOAD(0, kra, vra); NS_LSTORE(0, kra, vra);
;   if (ntl > 1) { NS_GLOAD(1, kra, vra); NS_LSTORE(1, kra, vra); }
;   __syncthreads();
;   f32x16 s0, s1, du0, du1; bf16x8 P[4];
;   int st_cur = 0;
.LBB0_938:
	s_add_i32 s91, s89, -1
	s_cmp_lt_u32 s91, s88
	s_cselect_b64 s[82:83], -1, 0
	s_mul_i32 s94, s6, 0x4800
	s_add_i32 s95, s94, 0
	v_mov_b32_e32 v139, s90
	v_add_u32_e32 v33, s95, v213
	ds_read_b32 v232, v139 offset:8
	ds_read_b32 v32, v139
	ds_read_b128 v[96:99], v33 offset:4608
	ds_read_b128 v[100:103], v33
	ds_read_b128 v[104:107], v33 offset:32
	ds_read_b128 v[108:111], v33 offset:4640
	ds_read_b128 v[112:115], v33 offset:64
	ds_read_b128 v[116:119], v33 offset:4672
	ds_read_b128 v[120:123], v33 offset:96
	ds_read_b128 v[124:127], v33 offset:4704
	s_cmp_ge_u32 s91, s88
	s_cbranch_scc1 .Lslc0_noload
	s_waitcnt lgkmcnt(9)
	v_readfirstlane_b32 s84, v232
	s_nop 1
	v_lshl_add_u32 v228, s84, 6, v212
	v_ashrrev_i32_e32 v229, 31, v228
	v_lshlrev_b64 v[228:229], 9, v[228:229]
	v_lshl_add_u64 v[230:231], v[194:195], 0, v[228:229]
	v_lshl_add_u64 v[228:229], v[196:197], 0, v[228:229]
	global_load_dwordx4 v[128:131], v[230:231], off
	global_load_dwordx4 v[132:135], v[228:229], off
.Lslc0_noload:
	s_waitcnt lgkmcnt(8)
	v_readfirstlane_b32 s84, v32
	s_nop 1
	v_lshrrev_b32_e32 v32, s84, v137
	v_and_b32_e32 v32, 1, v32
	v_cmp_eq_u32_e32 vcc, 1, v32
	s_nop 1
	v_cndmask_b32_e64 v32, v207, -v138, vcc
	v_mov_b32_e32 v33, v32
	v_mov_b32_e32 v34, v32
	v_mov_b32_e32 v35, v32
	v_mov_b32_e32 v36, v32
	v_mov_b32_e32 v37, v32
	v_mov_b32_e32 v38, v32
	v_mov_b32_e32 v39, v32
	v_mov_b32_e32 v40, v32
	v_mov_b32_e32 v41, v32
	v_mov_b32_e32 v42, v32
	v_mov_b32_e32 v43, v32
	v_mov_b32_e32 v44, v32
	v_mov_b32_e32 v45, v32
	v_mov_b32_e32 v46, v32
	v_mov_b32_e32 v47, v32
	s_setprio 1
	s_waitcnt lgkmcnt(6)
	v_mfma_f32_32x32x16_bf16 v[48:63], v[100:103], v[160:163], v[32:47]
	v_mfma_f32_32x32x16_bf16 v[32:47], v[96:99], v[160:163], v[32:47]
	s_waitcnt lgkmcnt(5)
	v_mfma_f32_32x32x16_bf16 v[48:63], v[104:107], v[168:171], v[48:63]
	s_waitcnt lgkmcnt(4)
	v_mfma_f32_32x32x16_bf16 v[32:47], v[108:111], v[168:171], v[32:47]
	s_waitcnt lgkmcnt(3)
	v_mfma_f32_32x32x16_bf16 v[48:63], v[112:115], v[164:167], v[48:63]
	s_waitcnt lgkmcnt(2)
	v_mfma_f32_32x32x16_bf16 v[32:47], v[116:119], v[164:167], v[32:47]
	s_waitcnt lgkmcnt(1)
	v_mfma_f32_32x32x16_bf16 v[48:63], v[120:123], v[172:175], v[48:63]
	s_waitcnt lgkmcnt(0)
	v_mfma_f32_32x32x16_bf16 v[32:47], v[124:127], v[172:175], v[32:47]
	s_setprio 0
	s_cmp_lg_u32 s84, s77
	s_cbranch_scc1 .LBB0_944
	s_and_b64 vcc, s[70:71], s[66:67]
	s_nop 7
	v_cndmask_b32_e32 v45, v45, v207, vcc
	s_and_b64 vcc, vcc, s[62:63]
	v_cndmask_b32_e32 v44, v44, v207, vcc
	s_and_b64 vcc, vcc, s[58:59]
	v_cndmask_b32_e32 v43, v43, v207, vcc
	s_and_b64 vcc, vcc, s[54:55]
	v_cndmask_b32_e32 v42, v42, v207, vcc
	s_and_b64 vcc, vcc, s[50:51]
	v_cndmask_b32_e32 v41, v41, v207, vcc
	s_and_b64 vcc, vcc, s[46:47]
	v_cndmask_b32_e32 v40, v40, v207, vcc
	s_and_b64 vcc, vcc, s[42:43]
	v_cndmask_b32_e32 v39, v39, v207, vcc
	s_and_b64 vcc, vcc, s[38:39]
	v_cndmask_b32_e32 v38, v38, v207, vcc
	s_and_b64 vcc, vcc, s[34:35]
	v_cndmask_b32_e32 v37, v37, v207, vcc
	s_and_b64 vcc, vcc, s[28:29]
	v_cndmask_b32_e32 v36, v36, v207, vcc
	s_and_b64 vcc, vcc, s[24:25]
	v_cndmask_b32_e32 v35, v35, v207, vcc
	s_and_b64 vcc, vcc, s[20:21]
	v_cndmask_b32_e32 v34, v34, v207, vcc
	s_and_b64 vcc, vcc, s[16:17]
	v_cndmask_b32_e32 v33, v33, v207, vcc
	s_and_b64 vcc, vcc, s[12:13]
	v_cndmask_b32_e64 v46, v46, v207, s[70:71]
	v_cndmask_b32_e32 v32, v32, v207, vcc
	s_and_saveexec_b64 s[84:85], s[74:75]
	s_mov_b32 s86, 0xf149f2ca
	v_mov_b32_e32 v47, s86
	s_or_b64 exec, exec, s[84:85]
	s_and_b64 vcc, s[72:73], s[68:69]
	v_cndmask_b32_e32 v62, v62, v207, vcc
	s_and_b64 vcc, vcc, s[64:65]
	v_cndmask_b32_e32 v61, v61, v207, vcc
	s_and_b64 vcc, vcc, s[60:61]
	v_cndmask_b32_e32 v60, v60, v207, vcc
	s_and_b64 vcc, vcc, s[56:57]
	v_cndmask_b32_e32 v59, v59, v207, vcc
	s_and_b64 vcc, vcc, s[52:53]
	v_cndmask_b32_e32 v58, v58, v207, vcc
	s_and_b64 vcc, vcc, s[48:49]
	v_cndmask_b32_e32 v57, v57, v207, vcc
	s_and_b64 vcc, vcc, s[44:45]
	v_cndmask_b32_e32 v56, v56, v207, vcc
	s_and_b64 vcc, vcc, s[40:41]
	v_cndmask_b32_e32 v55, v55, v207, vcc
	s_and_b64 vcc, vcc, s[36:37]
	v_cndmask_b32_e32 v54, v54, v207, vcc
	s_and_b64 vcc, vcc, s[30:31]
	v_cndmask_b32_e32 v53, v53, v207, vcc
	s_and_b64 vcc, vcc, s[26:27]
	v_cndmask_b32_e32 v52, v52, v207, vcc
	s_and_b64 vcc, vcc, s[22:23]
	v_cndmask_b32_e32 v51, v51, v207, vcc
	s_and_b64 vcc, vcc, s[18:19]
	v_cndmask_b32_e32 v50, v50, v207, vcc
	s_and_b64 vcc, vcc, s[14:15]
	v_cndmask_b32_e32 v49, v49, v207, vcc
	s_and_b64 vcc, vcc, s[10:11]
	v_cndmask_b32_e64 v63, v63, v207, s[72:73]
	v_cndmask_b32_e32 v48, v48, v207, vcc

; #define LAS __attribute__((address_space(3)))
; #define MFMA32(a, b, c) __builtin_amdgcn_mfma_f32_32x32x16_bf16((a), (b), (c), 0, 0, 0)
; #define SBAR() __builtin_amdgcn_sched_barrier(0)
; #define NS_GLOAD(k_, KR, VR) do { const int jj = __builtin_amdgcn_readfirstlane(jl[(k_)]); KR = *(const u32x4*)(kg + (size_t)(64 * jj + sr) * pitch + sc * 8); VR = *(const u32x4*)(vg + (size_t)(64 * jj + sr) * pitch + sc * 8); } while (0)
; #define NS_LSTORE(st_, KR, VR) do { lds8* b = lds + (st_) * NS_STAGE; *(LAS u32x4*)(b + sr * NS_STR + sc * 16) = KR; *(LAS u32x4*)(b + 64 * NS_STR + sr * NS_STR + sc * 16) = VR; } while (0)
; template <int KSTR> DI void qk64b(f32x16& s0, f32x16& s1, const lds8* kp, const bf16x8 (&q)[4], float bias) {
;   bf16x8 a[8];
; #pragma unroll
;   for (int ks = 0; ks < 4; ++ks) { a[2 * ks] = *(const LAS bf16x8*)(kp + ks * 32); a[2 * ks + 1] = *(const LAS bf16x8*)(kp + 32 * KSTR + ks * 32); }
; #pragma unroll
;   for (int i = 0; i < 16; ++i) { s0[i] = bias; s1[i] = bias; }
;   SBAR();
;   __builtin_amdgcn_s_setprio(1);
; #pragma unroll
;   for (int ks = 0; ks < 4; ++ks) { s0 = MFMA32(a[2 * ks], q[ks], s0); s1 = MFMA32(a[2 * ks + 1], q[ks], s1); }
;   __builtin_amdgcn_s_setprio(0);
;   SBAR();
; }
; template <int MODE>
; DI void nsa_branch(lds8* lds, const bf16_t* kg, const bf16_t* vg, int pitch, unsigned tiles, const bf16x8 (&q)[4], int qpos, unsigned mybits, int blk,
;                    f32x16 (&O)[2], float& muse, float& l, int tid, int lane, int grp, CmpCap& cap) {
;     ...
;   NS_GLOAD(0, kra, vra); NS_LSTORE(0, kra, vra);
;   if (ntl > 1) { NS_GLOAD(1, kra, vra); NS_LSTORE(1, kra, vra); }
;   __syncthreads();
;   f32x16 s0, s1, du0, du1; bf16x8 P[4];
;   int st_cur = 0;
.LBB0_953:
	v_add_f32_e32 v32, 0, v96
	v_add_f32_e32 v32, v97, v32
	v_add_f32_e32 v32, v98, v32
	v_add_f32_e32 v32, v99, v32
	v_add_f32_e32 v32, v100, v32
	v_add_f32_e32 v32, v101, v32
	v_add_f32_e32 v32, v102, v32
	v_add_f32_e32 v32, v103, v32
	v_add_f32_e32 v32, v104, v32
	v_add_f32_e32 v32, v105, v32
	v_add_f32_e32 v32, v106, v32
	v_add_f32_e32 v32, v107, v32
	v_add_f32_e32 v32, v108, v32
	v_add_f32_e32 v32, v109, v32
	v_add_f32_e32 v32, v110, v32
	v_add_f32_e32 v32, v111, v32
	v_add_f32_e32 v32, v112, v32
	v_add_f32_e32 v32, v113, v32
	v_add_f32_e32 v32, v114, v32
	v_add_f32_e32 v32, v115, v32
	v_add_f32_e32 v32, v116, v32
	v_add_f32_e32 v32, v117, v32
	v_add_f32_e32 v32, v118, v32
	v_add_f32_e32 v32, v119, v32
	v_add_f32_e32 v32, v120, v32
	v_add_f32_e32 v32, v121, v32
	v_add_f32_e32 v32, v122, v32
	v_add_f32_e32 v32, v123, v32
	v_add_f32_e32 v32, v124, v32
	v_add_f32_e32 v32, v125, v32
	v_add_f32_e32 v32, v126, v32
	v_add_f32_e32 v32, v127, v32
	s_add_i32 s84, s89, -2
	v_add_f32_e32 v139, v219, v32
	s_mov_b64 s[82:83], -1
	s_cmp_ge_u32 s84, s88
	s_mov_b64 s[84:85], -1
	s_movk_i32 s95, 0x1ff
	s_waitcnt lgkmcnt(0)
	s_barrier
	s_cbranch_scc1 .LBB0_937
	s_cmp_lt_u32 s89, s88
	s_cselect_b64 s[82:83], -1, 0
	s_add_i32 s84, s6, 1
	s_cmp_lg_u32 s6, 2
	s_cselect_b32 s6, s84, 0
	v_mov_b32_e32 v140, s90
	s_mul_i32 s86, s6, 0x4800
	s_add_i32 s87, s86, 0
	v_add_u32_e32 v60, s87, v213
	ds_read_b32 v232, v140 offset:12
	ds_read_b32 v233, v140 offset:4
	ds_read_b128 v[32:35], v60 offset:4608
	ds_read_b128 v[36:39], v60
	ds_read_b128 v[40:43], v60 offset:32
	ds_read_b128 v[44:47], v60 offset:4640
	ds_read_b128 v[48:51], v60 offset:64
	ds_read_b128 v[52:55], v60 offset:4672
	ds_read_b128 v[56:59], v60 offset:96
	ds_read_b128 v[60:63], v60 offset:4704
	s_cmp_ge_u32 s89, s88
	s_cbranch_scc1 .Lslc1_noload
	s_waitcnt lgkmcnt(9)
	v_readfirstlane_b32 s84, v232
	s_nop 1
	v_lshl_add_u32 v228, s84, 6, v212
	v_ashrrev_i32_e32 v229, 31, v228
	v_lshlrev_b64 v[228:229], 9, v[228:229]
	v_lshl_add_u64 v[230:231], v[194:195], 0, v[228:229]
	v_lshl_add_u64 v[228:229], v[196:197], 0, v[228:229]
	global_load_dwordx4 v[128:131], v[230:231], off
	global_load_dwordx4 v[132:135], v[228:229], off
.Lslc1_noload:
	s_waitcnt lgkmcnt(8)
	v_readfirstlane_b32 s84, v233
	s_nop 1
	v_lshrrev_b32_e32 v233, s84, v137
	v_and_b32_e32 v233, 1, v233
	v_cmp_eq_u32_e32 vcc, 1, v233
	s_nop 1
	v_cndmask_b32_e64 v96, v207, -v138, vcc
	v_mov_b32_e32 v97, v96
	v_mov_b32_e32 v98, v96
	v_mov_b32_e32 v99, v96
	v_mov_b32_e32 v100, v96
	v_mov_b32_e32 v101, v96
	v_mov_b32_e32 v102, v96
	v_mov_b32_e32 v103, v96
	v_mov_b32_e32 v104, v96
	v_mov_b32_e32 v105, v96
	v_mov_b32_e32 v106, v96
	v_mov_b32_e32 v107, v96
	v_mov_b32_e32 v108, v96
	v_mov_b32_e32 v109, v96
	v_mov_b32_e32 v110, v96
	v_mov_b32_e32 v111, v96
	s_setprio 1
	s_waitcnt lgkmcnt(6)
	v_mfma_f32_32x32x16_bf16 v[112:127], v[36:39], v[160:163], v[96:111]
	v_mfma_f32_32x32x16_bf16 v[96:111], v[32:35], v[160:163], v[96:111]
	s_waitcnt lgkmcnt(5)
	v_mfma_f32_32x32x16_bf16 v[112:127], v[40:43], v[168:171], v[112:127]
	s_waitcnt lgkmcnt(4)
	v_mfma_f32_32x32x16_bf16 v[96:111], v[44:47], v[168:171], v[96:111]
	s_waitcnt lgkmcnt(3)
	v_mfma_f32_32x32x16_bf16 v[112:127], v[48:51], v[164:167], v[112:127]
	s_waitcnt lgkmcnt(2)
	v_mfma_f32_32x32x16_bf16 v[96:111], v[52:55], v[164:167], v[96:111]
	s_waitcnt lgkmcnt(1)
	v_mfma_f32_32x32x16_bf16 v[112:127], v[56:59], v[172:175], v[112:127]
	s_waitcnt lgkmcnt(0)
	v_mfma_f32_32x32x16_bf16 v[96:111], v[60:63], v[172:175], v[96:111]
	s_setprio 0
	s_cmp_lg_u32 s84, s77
	s_cbranch_scc1 .LBB0_960
	s_and_b64 vcc, s[70:71], s[66:67]
	s_nop 7
	v_cndmask_b32_e32 v109, v109, v207, vcc
	s_and_b64 vcc, vcc, s[62:63]
	v_cndmask_b32_e32 v108, v108, v207, vcc
	s_and_b64 vcc, vcc, s[58:59]
	v_cndmask_b32_e32 v107, v107, v207, vcc
	s_and_b64 vcc, vcc, s[54:55]
	v_cndmask_b32_e32 v106, v106, v207, vcc
	s_and_b64 vcc, vcc, s[50:51]
	v_cndmask_b32_e32 v105, v105, v207, vcc
	s_and_b64 vcc, vcc, s[46:47]
	v_cndmask_b32_e32 v104, v104, v207, vcc
	s_and_b64 vcc, vcc, s[42:43]
	v_cndmask_b32_e32 v103, v103, v207, vcc
	s_and_b64 vcc, vcc, s[38:39]
	v_cndmask_b32_e32 v102, v102, v207, vcc
	s_and_b64 vcc, vcc, s[34:35]
	v_cndmask_b32_e32 v101, v101, v207, vcc
	s_and_b64 vcc, vcc, s[28:29]
	v_cndmask_b32_e32 v100, v100, v207, vcc
	s_and_b64 vcc, vcc, s[24:25]
	v_cndmask_b32_e32 v99, v99, v207, vcc
	s_and_b64 vcc, vcc, s[20:21]
	v_cndmask_b32_e32 v98, v98, v207, vcc
	s_and_b64 vcc, vcc, s[16:17]
	v_cndmask_b32_e32 v97, v97, v207, vcc
	s_and_b64 vcc, vcc, s[12:13]
	v_cndmask_b32_e64 v110, v110, v207, s[70:71]
	v_cndmask_b32_e32 v96, v96, v207, vcc
	s_and_saveexec_b64 s[84:85], s[74:75]
	s_mov_b32 s94, 0xf149f2ca
	v_mov_b32_e32 v111, s94
	s_or_b64 exec, exec, s[84:85]
	s_and_b64 vcc, s[72:73], s[68:69]
	v_cndmask_b32_e32 v126, v126, v207, vcc
	s_and_b64 vcc, vcc, s[64:65]
	v_cndmask_b32_e32 v125, v125, v207, vcc
	s_and_b64 vcc, vcc, s[60:61]
	v_cndmask_b32_e32 v124, v124, v207, vcc
	s_and_b64 vcc, vcc, s[56:57]
	v_cndmask_b32_e32 v123, v123, v207, vcc
	s_and_b64 vcc, vcc, s[52:53]
	v_cndmask_b32_e32 v122, v122, v207, vcc
	s_and_b64 vcc, vcc, s[48:49]
	v_cndmask_b32_e32 v121, v121, v207, vcc
	s_and_b64 vcc, vcc, s[44:45]
	v_cndmask_b32_e32 v120, v120, v207, vcc
	s_and_b64 vcc, vcc, s[40:41]
	v_cndmask_b32_e32 v119, v119, v207, vcc
	s_and_b64 vcc, vcc, s[36:37]
	v_cndmask_b32_e32 v118, v118, v207, vcc
	s_and_b64 vcc, vcc, s[30:31]
	v_cndmask_b32_e32 v117, v117, v207, vcc
	s_and_b64 vcc, vcc, s[26:27]
	v_cndmask_b32_e32 v116, v116, v207, vcc
	s_and_b64 vcc, vcc, s[22:23]
	v_cndmask_b32_e32 v115, v115, v207, vcc
	s_and_b64 vcc, vcc, s[18:19]
	v_cndmask_b32_e32 v114, v114, v207, vcc
	s_and_b64 vcc, vcc, s[14:15]
	v_cndmask_b32_e32 v113, v113, v207, vcc
	s_and_b64 vcc, vcc, s[10:11]
	v_cndmask_b32_e64 v127, v127, v207, s[72:73]
	v_cndmask_b32_e32 v112, v112, v207, vcc

; #define NS_GLOAD(k_, KR, VR) do { const int jj = __builtin_amdgcn_readfirstlane(jl[(k_)]); KR = *(const u32x4*)(kg + (size_t)(64 * jj + sr) * pitch + sc * 8); VR = *(const u32x4*)(vg + (size_t)(64 * jj + sr) * pitch + sc * 8); } while (0)
; #define NS_LSTORE(st_, KR, VR) do { lds8* b = lds + (st_) * NS_STAGE; *(LAS u32x4*)(b + sr * NS_STR + sc * 16) = KR; *(LAS u32x4*)(b + 64 * NS_STR + sr * NS_STR + sc * 16) = VR; } while (0)
; template <int MODE, int SLOT> DI void ns_valu(volatile LAS int* jl, int t, int ntl, int qpos, int h, int blk, f32x16& s0, f32x16& s1, f32x16& du0, f32x16& du1, f32x16 (&O)[2], float& muse, float& l, bf16x8 (&P)[4], CmpCap& cap) {
;     ...
;       } else {
;         if (j == blk || j + 8 == blk) {
;           const int lim = qpos - 64 * j - 4 * h, lo = lim - 512;
; #pragma unroll
;           for (int i = 0; i < 16; ++i) { const int ci = (i & 3) + 8 * (i >> 2); if (ci > lim || ci <= lo) s0[i] = NEG; if (ci + 32 > lim || ci + 32 <= lo) s1[i] = NEG; }
;         }
; template <int MODE>
; DI void nsa_branch(lds8* lds, const bf16_t* kg, const bf16_t* vg, int pitch, unsigned tiles, const bf16x8 (&q)[4], int qpos, unsigned mybits, int blk,
;                    f32x16 (&O)[2], float& muse, float& l, int tid, int lane, int grp, CmpCap& cap) {
;     ...
;   NS_GLOAD(0, kra, vra); NS_LSTORE(0, kra, vra);
;   if (ntl > 1) { NS_GLOAD(1, kra, vra); NS_LSTORE(1, kra, vra); }
;   __syncthreads();
;   f32x16 s0, s1, du0, du1; bf16x8 P[4];
;   int st_cur = 0;
.LBB0_981:
	s_add_i32 s47, s46, -1
	s_cmp_lt_u32 s47, s3
	s_cselect_b64 s[42:43], -1, 0
	s_mul_i32 s48, s6, 0x4800
	s_add_i32 s49, s48, 0
	v_mov_b32_e32 v96, s0
	v_add_u32_e32 v97, s49, v213
	ds_read_b32 v96, v96 offset:8
	ds_read_b128 v[130:133], v97
	ds_read_b128 v[134:137], v97 offset:32
	ds_read_b128 v[138:141], v97 offset:4608
	ds_read_b128 v[142:145], v97 offset:4640
	ds_read_b128 v[146:149], v97 offset:64
	ds_read_b128 v[150:153], v97 offset:96
	ds_read_b128 v[154:157], v97 offset:4672
	ds_read_b128 v[222:225], v97 offset:4704
	s_cmp_ge_u32 s47, s3
	s_cbranch_scc1 .Lwin0_noload
	s_waitcnt lgkmcnt(8)
	v_readfirstlane_b32 s8, v96
	s_nop 1
	v_lshl_add_u32 v96, s8, 6, v212
	v_ashrrev_i32_e32 v97, 31, v96
	v_lshlrev_b64 v[96:97], 9, v[96:97]
	v_lshl_add_u64 v[98:99], v[194:195], 0, v[96:97]
	v_lshl_add_u64 v[96:97], v[196:197], 0, v[96:97]
	global_load_dwordx4 v[176:179], v[98:99], off offset:256
	global_load_dwordx4 v[180:183], v[96:97], off offset:256
.Lwin0_noload:
	v_xor_b32_e32 v96, 0x80000000, v221
	v_mov_b32_e32 v97, v96
	v_mov_b32_e32 v98, v96
	v_mov_b32_e32 v99, v96
	v_mov_b32_e32 v100, v96
	v_mov_b32_e32 v101, v96
	v_mov_b32_e32 v102, v96
	v_mov_b32_e32 v103, v96
	v_mov_b32_e32 v104, v96
	v_mov_b32_e32 v105, v96
	v_mov_b32_e32 v106, v96
	v_mov_b32_e32 v107, v96
	v_mov_b32_e32 v108, v96
	v_mov_b32_e32 v109, v96
	v_mov_b32_e32 v110, v96
	v_mov_b32_e32 v111, v96
	s_setprio 1
	s_waitcnt lgkmcnt(7)
	v_mfma_f32_32x32x16_bf16 v[112:127], v[130:133], v[160:163], v[96:111]
	s_waitcnt lgkmcnt(5)
	v_mfma_f32_32x32x16_bf16 v[96:111], v[138:141], v[160:163], v[96:111]
	v_mfma_f32_32x32x16_bf16 v[112:127], v[134:137], v[168:171], v[112:127]
	s_waitcnt lgkmcnt(4)
	v_mfma_f32_32x32x16_bf16 v[96:111], v[142:145], v[168:171], v[96:111]
	s_waitcnt lgkmcnt(3)
	v_mfma_f32_32x32x16_bf16 v[112:127], v[146:149], v[164:167], v[112:127]
	s_waitcnt lgkmcnt(1)
	v_mfma_f32_32x32x16_bf16 v[96:111], v[154:157], v[164:167], v[96:111]
	v_mfma_f32_32x32x16_bf16 v[112:127], v[150:153], v[172:175], v[112:127]
	s_waitcnt lgkmcnt(0)
	v_mfma_f32_32x32x16_bf16 v[96:111], v[222:225], v[172:175], v[96:111]
	s_setprio 0
	v_mov_b32_e32 v129, s0
	ds_read_b32 v129, v129
	s_waitcnt lgkmcnt(0)
	v_readfirstlane_b32 s8, v129
	s_cmp_eq_u32 s8, s77
	s_cselect_b64 s[10:11], -1, 0
	s_add_i32 s9, s8, 8
	s_cmp_eq_u32 s9, s77
	s_cselect_b64 s[12:13], -1, 0
	s_or_b64 s[10:11], s[10:11], s[12:13]
	s_andn2_b64 vcc, exec, s[10:11]
	s_cbranch_vccnz .LBB0_987
	v_lshl_or_b32 v129, s8, 6, v214
	v_sub_u32_e32 v129, v211, v129
	v_subrev_u32_e32 v130, 32, v129
	v_cmp_gt_u32_e64 s[8:9], s33, v130
	v_add_u32_e32 v130, -1, v129
	v_cmp_gt_u32_e32 vcc, s33, v129
	v_cndmask_b32_e64 v96, v207, v96, s[8:9]
	v_cmp_gt_u32_e64 s[8:9], s33, v130
	v_subrev_u32_e32 v130, 33, v129
	v_cmp_gt_u32_e64 s[10:11], s33, v130
	v_add_u32_e32 v130, -2, v129
	s_nop 0
	v_cndmask_b32_e64 v97, v207, v97, s[10:11]
	v_cmp_gt_u32_e64 s[10:11], s33, v130
	v_subrev_u32_e32 v130, 34, v129
	v_cmp_gt_u32_e64 s[12:13], s33, v130
	v_add_u32_e32 v130, -3, v129
	s_nop 0
	v_cndmask_b32_e64 v98, v207, v98, s[12:13]
	v_cmp_gt_u32_e64 s[12:13], s33, v130
	v_subrev_u32_e32 v130, 35, v129
	v_cmp_gt_u32_e64 s[14:15], s33, v130
	v_add_u32_e32 v130, -8, v129
	s_nop 0
	v_cndmask_b32_e64 v99, v207, v99, s[14:15]
	v_cmp_gt_u32_e64 s[14:15], s33, v130
	v_subrev_u32_e32 v130, 40, v129
	v_cmp_gt_u32_e64 s[16:17], s33, v130
	v_add_u32_e32 v130, -9, v129
	s_nop 0
	v_cndmask_b32_e64 v100, v207, v100, s[16:17]
	v_cmp_gt_u32_e64 s[16:17], s33, v130
	v_subrev_u32_e32 v130, 41, v129
	v_cmp_gt_u32_e64 s[18:19], s33, v130
	v_add_u32_e32 v130, -10, v129
	s_nop 0
	v_cndmask_b32_e64 v101, v207, v101, s[18:19]
	v_cmp_gt_u32_e64 s[18:19], s33, v130
	v_subrev_u32_e32 v130, 42, v129
	v_cmp_gt_u32_e64 s[20:21], s33, v130
	v_add_u32_e32 v130, -11, v129
	s_nop 0
	v_cndmask_b32_e64 v102, v207, v102, s[20:21]
	v_cmp_gt_u32_e64 s[20:21], s33, v130
	v_subrev_u32_e32 v130, 43, v129
	v_cmp_gt_u32_e64 s[22:23], s33, v130
	v_add_u32_e32 v130, -16, v129
	s_nop 0
	v_cndmask_b32_e64 v103, v207, v103, s[22:23]
	v_cmp_gt_u32_e64 s[22:23], s33, v130
	v_subrev_u32_e32 v130, 48, v129
	v_cmp_gt_u32_e64 s[24:25], s33, v130
	v_subrev_u32_e32 v130, 17, v129
	s_nop 0
	v_cndmask_b32_e64 v104, v207, v104, s[24:25]
	v_cmp_gt_u32_e64 s[24:25], s33, v130
	v_subrev_u32_e32 v130, 49, v129
	v_cmp_gt_u32_e64 s[26:27], s33, v130
	v_subrev_u32_e32 v130, 18, v129
	s_nop 0
	v_cndmask_b32_e64 v105, v207, v105, s[26:27]
	v_cmp_gt_u32_e64 s[26:27], s33, v130
	v_subrev_u32_e32 v130, 50, v129
	v_cmp_gt_u32_e64 s[28:29], s33, v130
	v_subrev_u32_e32 v130, 19, v129
	s_nop 0
	v_cndmask_b32_e64 v106, v207, v106, s[28:29]
	v_cmp_gt_u32_e64 s[28:29], s33, v130
	v_subrev_u32_e32 v130, 51, v129
	v_cmp_gt_u32_e64 s[30:31], s33, v130
	v_subrev_u32_e32 v130, 24, v129
	s_nop 0
	v_cndmask_b32_e64 v107, v207, v107, s[30:31]
	v_cmp_gt_u32_e64 s[30:31], s33, v130
	v_subrev_u32_e32 v130, 56, v129
	v_cmp_gt_u32_e64 s[34:35], s33, v130
	v_subrev_u32_e32 v130, 25, v129
	s_nop 0
	v_cndmask_b32_e64 v108, v207, v108, s[34:35]
	v_cmp_gt_u32_e64 s[34:35], s33, v130
	v_subrev_u32_e32 v130, 57, v129
	v_cmp_gt_u32_e64 s[36:37], s33, v130
	v_subrev_u32_e32 v130, 26, v129
	s_nop 0
	v_cndmask_b32_e64 v109, v207, v109, s[36:37]
	v_cmp_gt_u32_e64 s[36:37], s33, v130
	v_subrev_u32_e32 v130, 58, v129
	v_cmp_gt_u32_e64 s[38:39], s33, v130
	v_subrev_u32_e32 v130, 27, v129
	v_subrev_u32_e32 v129, 59, v129
	v_cndmask_b32_e64 v110, v207, v110, s[38:39]
	v_cmp_gt_u32_e64 s[38:39], s33, v130
	v_cmp_lt_u32_e64 s[40:41], s95, v129
	s_and_saveexec_b64 s[44:45], s[40:41]
	s_mov_b32 s1, 0xf149f2ca
	v_mov_b32_e32 v111, s1
	s_or_b64 exec, exec, s[44:45]
	v_cndmask_b32_e32 v112, v207, v112, vcc
	v_cndmask_b32_e64 v113, v207, v113, s[8:9]
	v_cndmask_b32_e64 v114, v207, v114, s[10:11]
	v_cndmask_b32_e64 v115, v207, v115, s[12:13]
	v_cndmask_b32_e64 v116, v207, v116, s[14:15]
	v_cndmask_b32_e64 v117, v207, v117, s[16:17]
	v_cndmask_b32_e64 v118, v207, v118, s[18:19]
	v_cndmask_b32_e64 v119, v207, v119, s[20:21]
	v_cndmask_b32_e64 v120, v207, v120, s[22:23]
	v_cndmask_b32_e64 v121, v207, v121, s[24:25]
	v_cndmask_b32_e64 v122, v207, v122, s[26:27]
	v_cndmask_b32_e64 v123, v207, v123, s[28:29]
	v_cndmask_b32_e64 v124, v207, v124, s[30:31]
	v_cndmask_b32_e64 v125, v207, v125, s[34:35]
	v_cndmask_b32_e64 v126, v207, v126, s[36:37]
	v_cndmask_b32_e64 v127, v207, v127, s[38:39]

; #define NS_GLOAD(k_, KR, VR) do { const int jj = __builtin_amdgcn_readfirstlane(jl[(k_)]); KR = *(const u32x4*)(kg + (size_t)(64 * jj + sr) * pitch + sc * 8); VR = *(const u32x4*)(vg + (size_t)(64 * jj + sr) * pitch + sc * 8); } while (0)
; #define NS_LSTORE(st_, KR, VR) do { lds8* b = lds + (st_) * NS_STAGE; *(LAS u32x4*)(b + sr * NS_STR + sc * 16) = KR; *(LAS u32x4*)(b + 64 * NS_STR + sr * NS_STR + sc * 16) = VR; } while (0)
; template <int NDVB, bool HAS_NEXT> DI void softmax_def(f32x16& sa0, f32x16& sa1, f32x16& sb0, f32x16& sb1, f32x16 (&O)[NDVB], float& muse, float& l, bool first, bf16x8 (&P)[4], bool check = true) {
;     ...
;   float sum = 0.f;
; #pragma unroll
;   for (int i = 0; i < 16; ++i) { sa0[i] = __builtin_amdgcn_exp2f(sa0[i]); sum += sa0[i]; }
; #pragma unroll
;   for (int i = 0; i < 16; ++i) { sa1[i] = __builtin_amdgcn_exp2f(sa1[i]); sum += sa1[i]; }
;   l += sum;
; template <int MODE>
; DI void nsa_branch(lds8* lds, const bf16_t* kg, const bf16_t* vg, int pitch, unsigned tiles, const bf16x8 (&q)[4], int qpos, unsigned mybits, int blk,
;                    f32x16 (&O)[2], float& muse, float& l, int tid, int lane, int grp, CmpCap& cap) {
;     ...
;   NS_GLOAD(0, kra, vra); NS_LSTORE(0, kra, vra);
;   if (ntl > 1) { NS_GLOAD(1, kra, vra); NS_LSTORE(1, kra, vra); }
;   __syncthreads();
;   f32x16 s0, s1, du0, du1; bf16x8 P[4];
;   int st_cur = 0;
.LBB0_996:
	v_add_f32_e32 v96, 0, v129
	v_add_f32_e32 v96, v130, v96
	v_add_f32_e32 v96, v131, v96
	v_add_f32_e32 v96, v132, v96
	v_add_f32_e32 v96, v133, v96
	v_add_f32_e32 v96, v134, v96
	v_add_f32_e32 v96, v135, v96
	v_add_f32_e32 v96, v136, v96
	v_add_f32_e32 v96, v137, v96
	v_add_f32_e32 v96, v138, v96
	v_add_f32_e32 v96, v139, v96
	v_add_f32_e32 v96, v140, v96
	v_add_f32_e32 v96, v141, v96
	v_add_f32_e32 v96, v142, v96
	v_add_f32_e32 v96, v143, v96
	v_add_f32_e32 v96, v144, v96
	v_add_f32_e32 v96, v145, v96
	v_add_f32_e32 v96, v146, v96
	v_add_f32_e32 v96, v147, v96
	v_add_f32_e32 v96, v148, v96
	v_add_f32_e32 v96, v149, v96
	v_add_f32_e32 v96, v150, v96
	v_add_f32_e32 v96, v151, v96
	v_add_f32_e32 v96, v152, v96
	v_add_f32_e32 v96, v153, v96
	v_add_f32_e32 v96, v154, v96
	v_add_f32_e32 v96, v155, v96
	v_add_f32_e32 v96, v156, v96
	v_add_f32_e32 v96, v157, v96
	v_add_f32_e32 v96, v158, v96
	v_add_f32_e32 v96, v159, v96
	v_add_f32_e32 v96, v222, v96
	s_add_i32 s10, s46, -2
	v_add_f32_e32 v222, v128, v96
	s_mov_b64 s[8:9], -1
	s_cmp_ge_u32 s10, s3
	s_mov_b64 s[10:11], -1
	s_waitcnt lgkmcnt(0)
	s_barrier
	s_cbranch_scc1 .LBB0_980
	s_cmp_lt_u32 s46, s3
	s_cselect_b64 s[42:43], -1, 0
	s_add_i32 s8, s6, 1
	s_cmp_lg_u32 s6, 2
	s_cselect_b32 s6, s8, 0
	s_mul_i32 s48, s6, 0x4800
	s_add_i32 s49, s48, 0
	v_mov_b32_e32 v128, s0
	v_add_u32_e32 v124, s49, v213
	ds_read_b32 v128, v128 offset:12
	ds_read_b128 v[96:99], v124
	ds_read_b128 v[100:103], v124 offset:32
	ds_read_b128 v[104:107], v124 offset:4608
	ds_read_b128 v[108:111], v124 offset:4640
	ds_read_b128 v[112:115], v124 offset:64
	ds_read_b128 v[116:119], v124 offset:96
	ds_read_b128 v[120:123], v124 offset:4672
	ds_read_b128 v[124:127], v124 offset:4704
	s_cmp_ge_u32 s46, s3
	s_cbranch_scc1 .Lwin1_noload
	s_waitcnt lgkmcnt(8)
	v_readfirstlane_b32 s8, v128
	s_nop 1
	v_lshl_add_u32 v128, s8, 6, v212
	v_ashrrev_i32_e32 v129, 31, v128
	v_lshlrev_b64 v[128:129], 9, v[128:129]
	v_lshl_add_u64 v[130:131], v[194:195], 0, v[128:129]
	v_lshl_add_u64 v[128:129], v[196:197], 0, v[128:129]
	global_load_dwordx4 v[176:179], v[130:131], off offset:256
	global_load_dwordx4 v[180:183], v[128:129], off offset:256
; #define LAS __attribute__((address_space(3)))
; #define MFMA32(a, b, c) __builtin_amdgcn_mfma_f32_32x32x16_bf16((a), (b), (c), 0, 0, 0)
; #define SBAR() __builtin_amdgcn_sched_barrier(0)
; template <int KSTR> DI void qk64b(f32x16& s0, f32x16& s1, const lds8* kp, const bf16x8 (&q)[4], float bias) {
;   bf16x8 a[8];
; #pragma unroll
;   for (int ks = 0; ks < 4; ++ks) { a[2 * ks] = *(const LAS bf16x8*)(kp + ks * 32); a[2 * ks + 1] = *(const LAS bf16x8*)(kp + 32 * KSTR + ks * 32); }
; #pragma unroll
;   for (int i = 0; i < 16; ++i) { s0[i] = bias; s1[i] = bias; }
;   SBAR();
;   __builtin_amdgcn_s_setprio(1);
; #pragma unroll
;   for (int ks = 0; ks < 4; ++ks) { s0 = MFMA32(a[2 * ks], q[ks], s0); s1 = MFMA32(a[2 * ks + 1], q[ks], s1); }
;   __builtin_amdgcn_s_setprio(0);
;   SBAR();
; }
; template <int MODE, int SLOT> DI void ns_valu(volatile LAS int* jl, int t, int ntl, int qpos, int h, int blk, f32x16& s0, f32x16& s1, f32x16& du0, f32x16& du1, f32x16 (&O)[2], float& muse, float& l, bf16x8 (&P)[4], CmpCap& cap) {
;     ...
;       } else {
;         if (j == blk || j + 8 == blk) {
;           const int lim = qpos - 64 * j - 4 * h, lo = lim - 512;
; #pragma unroll
;           for (int i = 0; i < 16; ++i) { const int ci = (i & 3) + 8 * (i >> 2); if (ci > lim || ci <= lo) s0[i] = NEG; if (ci + 32 > lim || ci + 32 <= lo) s1[i] = NEG; }
;         }
.Lwin1_noload:
	v_xor_b32_e32 v128, 0x80000000, v221
	v_mov_b32_e32 v129, v128
	v_mov_b32_e32 v130, v128
	v_mov_b32_e32 v131, v128
	v_mov_b32_e32 v132, v128
	v_mov_b32_e32 v133, v128
	v_mov_b32_e32 v134, v128
	v_mov_b32_e32 v135, v128
	v_mov_b32_e32 v136, v128
	v_mov_b32_e32 v137, v128
	v_mov_b32_e32 v138, v128
	v_mov_b32_e32 v139, v128
	v_mov_b32_e32 v140, v128
	v_mov_b32_e32 v141, v128
	v_mov_b32_e32 v142, v128
	v_mov_b32_e32 v143, v128
	s_setprio 1
	s_waitcnt lgkmcnt(7)
	v_mfma_f32_32x32x16_bf16 v[144:159], v[96:99], v[160:163], v[128:143]
	s_waitcnt lgkmcnt(5)
	v_mfma_f32_32x32x16_bf16 v[128:143], v[104:107], v[160:163], v[128:143]
	v_mfma_f32_32x32x16_bf16 v[144:159], v[100:103], v[168:171], v[144:159]
	s_waitcnt lgkmcnt(4)
	v_mfma_f32_32x32x16_bf16 v[128:143], v[108:111], v[168:171], v[128:143]
	s_waitcnt lgkmcnt(3)
	v_mfma_f32_32x32x16_bf16 v[144:159], v[112:115], v[164:167], v[144:159]
	s_waitcnt lgkmcnt(1)
	v_mfma_f32_32x32x16_bf16 v[128:143], v[120:123], v[164:167], v[128:143]
	v_mfma_f32_32x32x16_bf16 v[144:159], v[116:119], v[172:175], v[144:159]
	s_waitcnt lgkmcnt(0)
	v_mfma_f32_32x32x16_bf16 v[128:143], v[124:127], v[172:175], v[128:143]
	s_setprio 0
	v_mov_b32_e32 v96, s0
	ds_read_b32 v96, v96 offset:4
	s_waitcnt lgkmcnt(0)
	v_readfirstlane_b32 s8, v96
	s_cmp_eq_u32 s8, s77
	s_cselect_b64 s[10:11], -1, 0
	s_add_i32 s9, s8, 8
	s_cmp_eq_u32 s9, s77
	s_cselect_b64 s[12:13], -1, 0
	s_or_b64 s[10:11], s[10:11], s[12:13]
	s_andn2_b64 vcc, exec, s[10:11]
	s_cbranch_vccnz .LBB0_1003
	v_lshl_or_b32 v96, s8, 6, v214
	v_sub_u32_e32 v96, v211, v96
	v_subrev_u32_e32 v97, 32, v96
	v_cmp_gt_u32_e64 s[8:9], s33, v97
	v_add_u32_e32 v97, -1, v96
	v_cmp_gt_u32_e32 vcc, s33, v96
	v_cndmask_b32_e64 v128, v207, v128, s[8:9]
	v_cmp_gt_u32_e64 s[8:9], s33, v97
	v_subrev_u32_e32 v97, 33, v96
	v_cmp_gt_u32_e64 s[10:11], s33, v97
	v_add_u32_e32 v97, -2, v96
	s_nop 0
	v_cndmask_b32_e64 v129, v207, v129, s[10:11]
	v_cmp_gt_u32_e64 s[10:11], s33, v97
	v_subrev_u32_e32 v97, 34, v96
	v_cmp_gt_u32_e64 s[12:13], s33, v97
	v_add_u32_e32 v97, -3, v96
	s_nop 0
	v_cndmask_b32_e64 v130, v207, v130, s[12:13]
	v_cmp_gt_u32_e64 s[12:13], s33, v97
	v_subrev_u32_e32 v97, 35, v96
	v_cmp_gt_u32_e64 s[14:15], s33, v97
	v_add_u32_e32 v97, -8, v96
	s_nop 0
	v_cndmask_b32_e64 v131, v207, v131, s[14:15]
	v_cmp_gt_u32_e64 s[14:15], s33, v97
	v_subrev_u32_e32 v97, 40, v96
	v_cmp_gt_u32_e64 s[16:17], s33, v97
	v_add_u32_e32 v97, -9, v96
	s_nop 0
	v_cndmask_b32_e64 v132, v207, v132, s[16:17]
	v_cmp_gt_u32_e64 s[16:17], s33, v97
	v_subrev_u32_e32 v97, 41, v96
	v_cmp_gt_u32_e64 s[18:19], s33, v97
	v_add_u32_e32 v97, -10, v96
	s_nop 0
	v_cndmask_b32_e64 v133, v207, v133, s[18:19]
	v_cmp_gt_u32_e64 s[18:19], s33, v97
	v_subrev_u32_e32 v97, 42, v96
	v_cmp_gt_u32_e64 s[20:21], s33, v97
	v_add_u32_e32 v97, -11, v96
	s_nop 0
	v_cndmask_b32_e64 v134, v207, v134, s[20:21]
	v_cmp_gt_u32_e64 s[20:21], s33, v97
	v_subrev_u32_e32 v97, 43, v96
	v_cmp_gt_u32_e64 s[22:23], s33, v97
	v_add_u32_e32 v97, -16, v96
	s_nop 0
	v_cndmask_b32_e64 v135, v207, v135, s[22:23]
	v_cmp_gt_u32_e64 s[22:23], s33, v97
	v_subrev_u32_e32 v97, 48, v96
	v_cmp_gt_u32_e64 s[24:25], s33, v97
	v_subrev_u32_e32 v97, 17, v96
	s_nop 0
	v_cndmask_b32_e64 v136, v207, v136, s[24:25]
	v_cmp_gt_u32_e64 s[24:25], s33, v97
	v_subrev_u32_e32 v97, 49, v96
	v_cmp_gt_u32_e64 s[26:27], s33, v97
	v_subrev_u32_e32 v97, 18, v96
	s_nop 0
	v_cndmask_b32_e64 v137, v207, v137, s[26:27]
	v_cmp_gt_u32_e64 s[26:27], s33, v97
	v_subrev_u32_e32 v97, 50, v96
	v_cmp_gt_u32_e64 s[28:29], s33, v97
	v_subrev_u32_e32 v97, 19, v96
	s_nop 0
	v_cndmask_b32_e64 v138, v207, v138, s[28:29]
	v_cmp_gt_u32_e64 s[28:29], s33, v97
	v_subrev_u32_e32 v97, 51, v96
	v_cmp_gt_u32_e64 s[30:31], s33, v97
	v_subrev_u32_e32 v97, 24, v96
	s_nop 0
	v_cndmask_b32_e64 v139, v207, v139, s[30:31]
	v_cmp_gt_u32_e64 s[30:31], s33, v97
	v_subrev_u32_e32 v97, 56, v96
	v_cmp_gt_u32_e64 s[34:35], s33, v97
	v_subrev_u32_e32 v97, 25, v96
	s_nop 0
	v_cndmask_b32_e64 v140, v207, v140, s[34:35]
	v_cmp_gt_u32_e64 s[34:35], s33, v97
	v_subrev_u32_e32 v97, 57, v96
	v_cmp_gt_u32_e64 s[36:37], s33, v97
	v_subrev_u32_e32 v97, 26, v96
	s_nop 0
	v_cndmask_b32_e64 v141, v207, v141, s[36:37]
	v_cmp_gt_u32_e64 s[36:37], s33, v97
	v_subrev_u32_e32 v97, 58, v96
	v_cmp_gt_u32_e64 s[38:39], s33, v97
	v_subrev_u32_e32 v97, 27, v96
	v_subrev_u32_e32 v96, 59, v96
	v_cndmask_b32_e64 v142, v207, v142, s[38:39]
	v_cmp_gt_u32_e64 s[38:39], s33, v97
	v_cmp_lt_u32_e64 s[40:41], s95, v96
	s_and_saveexec_b64 s[44:45], s[40:41]
	s_mov_b32 s1, 0xf149f2ca
	v_mov_b32_e32 v143, s1
	s_or_b64 exec, exec, s[44:45]
	v_cndmask_b32_e32 v144, v207, v144, vcc
	v_cndmask_b32_e64 v145, v207, v145, s[8:9]
	v_cndmask_b32_e64 v146, v207, v146, s[10:11]
	v_cndmask_b32_e64 v147, v207, v147, s[12:13]
	v_cndmask_b32_e64 v148, v207, v148, s[14:15]
	v_cndmask_b32_e64 v149, v207, v149, s[16:17]
	v_cndmask_b32_e64 v150, v207, v150, s[18:19]
	v_cndmask_b32_e64 v151, v207, v151, s[20:21]
	v_cndmask_b32_e64 v152, v207, v152, s[22:23]
	v_cndmask_b32_e64 v153, v207, v153, s[24:25]
	v_cndmask_b32_e64 v154, v207, v154, s[26:27]
	v_cndmask_b32_e64 v155, v207, v155, s[28:29]
	v_cndmask_b32_e64 v156, v207, v156, s[30:31]
	v_cndmask_b32_e64 v157, v207, v157, s[34:35]
	v_cndmask_b32_e64 v158, v207, v158, s[36:37]
	v_cndmask_b32_e64 v159, v207, v159, s[38:39]
